# RWKV step loop: state register pairs hold one column of both rows (broadcast op_sel), dot products need no lo+hi combine adds; single accumulation chains interleaved with the rank-1 updates
# speedup vs baseline: 1.0026x; 1.0026x over previous
.Lrwkv_step2:
	s_waitcnt lgkmcnt(10)
	v_pk_mul_f32 v[216:217], v[130:131], v[0:1] op_sel:[0,0] op_sel_hi:[1,0]
	s_nop 0
	v_pk_fma_f32 v[216:217], v[132:133], v[0:1], v[216:217] op_sel:[0,1,0] op_sel_hi:[1,1,1]
	v_pk_fma_f32 v[130:131], v[146:147], v[56:57], v[130:131] op_sel:[0,0,0] op_sel_hi:[1,0,1]
	v_pk_fma_f32 v[216:217], v[134:135], v[2:3], v[216:217] op_sel:[0,0,0] op_sel_hi:[1,0,1]
	v_pk_fma_f32 v[132:133], v[146:147], v[56:57], v[132:133] op_sel:[0,1,0] op_sel_hi:[1,1,1]
	v_pk_fma_f32 v[216:217], v[136:137], v[2:3], v[216:217] op_sel:[0,1,0] op_sel_hi:[1,1,1]
	v_pk_fma_f32 v[134:135], v[146:147], v[58:59], v[134:135] op_sel:[0,0,0] op_sel_hi:[1,0,1]
	v_pk_fma_f32 v[216:217], v[138:139], v[4:5], v[216:217] op_sel:[0,0,0] op_sel_hi:[1,0,1]
	v_pk_fma_f32 v[136:137], v[146:147], v[58:59], v[136:137] op_sel:[0,1,0] op_sel_hi:[1,1,1]
	v_pk_fma_f32 v[216:217], v[140:141], v[4:5], v[216:217] op_sel:[0,1,0] op_sel_hi:[1,1,1]
	v_pk_fma_f32 v[138:139], v[146:147], v[60:61], v[138:139] op_sel:[0,0,0] op_sel_hi:[1,0,1]
	v_pk_fma_f32 v[216:217], v[142:143], v[6:7], v[216:217] op_sel:[0,0,0] op_sel_hi:[1,0,1]
	v_pk_fma_f32 v[140:141], v[146:147], v[60:61], v[140:141] op_sel:[0,1,0] op_sel_hi:[1,1,1]
	v_pk_fma_f32 v[216:217], v[144:145], v[6:7], v[216:217] op_sel:[0,1,0] op_sel_hi:[1,1,1]
	v_pk_fma_f32 v[142:143], v[146:147], v[62:63], v[142:143] op_sel:[0,0,0] op_sel_hi:[1,0,1]
	v_pk_fma_f32 v[144:145], v[146:147], v[62:63], v[144:145] op_sel:[0,1,0] op_sel_hi:[1,1,1]
	v_add_f32_dpp v216, v216, v216 quad_perm:[1,0,3,2] row_mask:0xf bank_mask:0xf bound_ctrl:1
	v_add_f32_dpp v217, v217, v217 quad_perm:[1,0,3,2] row_mask:0xf bank_mask:0xf bound_ctrl:1
	ds_read_b128 v[0:3], v112 offset:16896
	v_add_f32_dpp v216, v216, v216 quad_perm:[2,3,0,1] row_mask:0xf bank_mask:0xf bound_ctrl:1
	v_add_f32_dpp v217, v217, v217 quad_perm:[2,3,0,1] row_mask:0xf bank_mask:0xf bound_ctrl:1
	ds_read_b128 v[4:7], v112 offset:16912
	v_add_f32_dpp v216, v216, v216 row_half_mirror row_mask:0xf bank_mask:0xf bound_ctrl:1
	v_add_f32_dpp v217, v217, v217 row_half_mirror row_mask:0xf bank_mask:0xf bound_ctrl:1
	v_pk_fma_f32 v[130:131], v[216:217], v[48:49], v[130:131] op_sel:[0,0,0] op_sel_hi:[1,0,1]
	v_pk_fma_f32 v[132:133], v[216:217], v[48:49], v[132:133] op_sel:[0,1,0] op_sel_hi:[1,1,1]
	v_pk_mul_f32 v[238:239], v[130:131], v[64:65] op_sel:[0,0] op_sel_hi:[1,0]
	v_pk_fma_f32 v[134:135], v[216:217], v[50:51], v[134:135] op_sel:[0,0,0] op_sel_hi:[1,0,1]
	v_pk_fma_f32 v[238:239], v[132:133], v[64:65], v[238:239] op_sel:[0,1,0] op_sel_hi:[1,1,1]
	v_pk_fma_f32 v[136:137], v[216:217], v[50:51], v[136:137] op_sel:[0,1,0] op_sel_hi:[1,1,1]
	v_pk_fma_f32 v[238:239], v[134:135], v[66:67], v[238:239] op_sel:[0,0,0] op_sel_hi:[1,0,1]
	v_pk_fma_f32 v[138:139], v[216:217], v[52:53], v[138:139] op_sel:[0,0,0] op_sel_hi:[1,0,1]
	v_pk_fma_f32 v[238:239], v[136:137], v[66:67], v[238:239] op_sel:[0,1,0] op_sel_hi:[1,1,1]
	v_pk_fma_f32 v[140:141], v[216:217], v[52:53], v[140:141] op_sel:[0,1,0] op_sel_hi:[1,1,1]
	v_pk_fma_f32 v[238:239], v[138:139], v[68:69], v[238:239] op_sel:[0,0,0] op_sel_hi:[1,0,1]
	v_pk_fma_f32 v[142:143], v[216:217], v[54:55], v[142:143] op_sel:[0,0,0] op_sel_hi:[1,0,1]
	v_pk_fma_f32 v[238:239], v[140:141], v[68:69], v[238:239] op_sel:[0,1,0] op_sel_hi:[1,1,1]
	v_pk_fma_f32 v[144:145], v[216:217], v[54:55], v[144:145] op_sel:[0,1,0] op_sel_hi:[1,1,1]
	v_pk_fma_f32 v[238:239], v[142:143], v[70:71], v[238:239] op_sel:[0,0,0] op_sel_hi:[1,0,1]
	ds_read_b128 v[48:51], v112 offset:25088
	v_pk_fma_f32 v[238:239], v[144:145], v[70:71], v[238:239] op_sel:[0,1,0] op_sel_hi:[1,1,1]
	ds_read_b128 v[52:55], v112 offset:25104
	ds_read_b128 v[56:59], v112 offset:8704
	v_add_f32_dpp v238, v238, v238 quad_perm:[1,0,3,2] row_mask:0xf bank_mask:0xf bound_ctrl:1
	v_add_f32_dpp v239, v239, v239 quad_perm:[1,0,3,2] row_mask:0xf bank_mask:0xf bound_ctrl:1
	ds_read_b128 v[60:63], v112 offset:8720
	v_add_f32_dpp v238, v238, v238 quad_perm:[2,3,0,1] row_mask:0xf bank_mask:0xf bound_ctrl:1
	v_add_f32_dpp v239, v239, v239 quad_perm:[2,3,0,1] row_mask:0xf bank_mask:0xf bound_ctrl:1
	ds_read_b128 v[64:67], v112 offset:33280
	v_add_f32_dpp v238, v238, v238 row_half_mirror row_mask:0xf bank_mask:0xf bound_ctrl:1
	v_add_f32_dpp v239, v239, v239 row_half_mirror row_mask:0xf bank_mask:0xf bound_ctrl:1
	ds_read_b128 v[68:71], v112 offset:33296
	ds_read_b64 v[146:147], v214 offset:41472
	s_and_saveexec_b64 s[36:37], s[8:9]
	ds_write_b64 v214, v[238:239] offset:49152
	s_or_b64 exec, exec, s[36:37]
	s_waitcnt lgkmcnt(10)
	v_pk_mul_f32 v[216:217], v[130:131], v[72:73] op_sel:[0,0] op_sel_hi:[1,0]
	s_nop 0
	v_pk_fma_f32 v[216:217], v[132:133], v[72:73], v[216:217] op_sel:[0,1,0] op_sel_hi:[1,1,1]
	v_pk_fma_f32 v[130:131], v[148:149], v[96:97], v[130:131] op_sel:[0,0,0] op_sel_hi:[1,0,1]
	v_pk_fma_f32 v[216:217], v[134:135], v[74:75], v[216:217] op_sel:[0,0,0] op_sel_hi:[1,0,1]
	v_pk_fma_f32 v[132:133], v[148:149], v[96:97], v[132:133] op_sel:[0,1,0] op_sel_hi:[1,1,1]
	v_pk_fma_f32 v[216:217], v[136:137], v[74:75], v[216:217] op_sel:[0,1,0] op_sel_hi:[1,1,1]
	v_pk_fma_f32 v[134:135], v[148:149], v[98:99], v[134:135] op_sel:[0,0,0] op_sel_hi:[1,0,1]
	v_pk_fma_f32 v[216:217], v[138:139], v[76:77], v[216:217] op_sel:[0,0,0] op_sel_hi:[1,0,1]
	v_pk_fma_f32 v[136:137], v[148:149], v[98:99], v[136:137] op_sel:[0,1,0] op_sel_hi:[1,1,1]
	v_pk_fma_f32 v[216:217], v[140:141], v[76:77], v[216:217] op_sel:[0,1,0] op_sel_hi:[1,1,1]
	v_pk_fma_f32 v[138:139], v[148:149], v[100:101], v[138:139] op_sel:[0,0,0] op_sel_hi:[1,0,1]
	v_pk_fma_f32 v[216:217], v[142:143], v[78:79], v[216:217] op_sel:[0,0,0] op_sel_hi:[1,0,1]
	v_pk_fma_f32 v[140:141], v[148:149], v[100:101], v[140:141] op_sel:[0,1,0] op_sel_hi:[1,1,1]
	v_pk_fma_f32 v[216:217], v[144:145], v[78:79], v[216:217] op_sel:[0,1,0] op_sel_hi:[1,1,1]
	v_pk_fma_f32 v[142:143], v[148:149], v[102:103], v[142:143] op_sel:[0,0,0] op_sel_hi:[1,0,1]
	v_pk_fma_f32 v[144:145], v[148:149], v[102:103], v[144:145] op_sel:[0,1,0] op_sel_hi:[1,1,1]
	v_add_f32_dpp v216, v216, v216 quad_perm:[1,0,3,2] row_mask:0xf bank_mask:0xf bound_ctrl:1
	v_add_f32_dpp v217, v217, v217 quad_perm:[1,0,3,2] row_mask:0xf bank_mask:0xf bound_ctrl:1
	ds_read_b128 v[72:75], v112 offset:17152
	v_add_f32_dpp v216, v216, v216 quad_perm:[2,3,0,1] row_mask:0xf bank_mask:0xf bound_ctrl:1
	v_add_f32_dpp v217, v217, v217 quad_perm:[2,3,0,1] row_mask:0xf bank_mask:0xf bound_ctrl:1
	ds_read_b128 v[76:79], v112 offset:17168
	v_add_f32_dpp v216, v216, v216 row_half_mirror row_mask:0xf bank_mask:0xf bound_ctrl:1
	v_add_f32_dpp v217, v217, v217 row_half_mirror row_mask:0xf bank_mask:0xf bound_ctrl:1
	v_pk_fma_f32 v[130:131], v[216:217], v[88:89], v[130:131] op_sel:[0,0,0] op_sel_hi:[1,0,1]
	v_pk_fma_f32 v[132:133], v[216:217], v[88:89], v[132:133] op_sel:[0,1,0] op_sel_hi:[1,1,1]
	v_pk_mul_f32 v[238:239], v[130:131], v[104:105] op_sel:[0,0] op_sel_hi:[1,0]
	v_pk_fma_f32 v[134:135], v[216:217], v[90:91], v[134:135] op_sel:[0,0,0] op_sel_hi:[1,0,1]
	v_pk_fma_f32 v[238:239], v[132:133], v[104:105], v[238:239] op_sel:[0,1,0] op_sel_hi:[1,1,1]
	v_pk_fma_f32 v[136:137], v[216:217], v[90:91], v[136:137] op_sel:[0,1,0] op_sel_hi:[1,1,1]
	v_pk_fma_f32 v[238:239], v[134:135], v[106:107], v[238:239] op_sel:[0,0,0] op_sel_hi:[1,0,1]
	v_pk_fma_f32 v[138:139], v[216:217], v[92:93], v[138:139] op_sel:[0,0,0] op_sel_hi:[1,0,1]
	v_pk_fma_f32 v[238:239], v[136:137], v[106:107], v[238:239] op_sel:[0,1,0] op_sel_hi:[1,1,1]
	v_pk_fma_f32 v[140:141], v[216:217], v[92:93], v[140:141] op_sel:[0,1,0] op_sel_hi:[1,1,1]
	v_pk_fma_f32 v[238:239], v[138:139], v[108:109], v[238:239] op_sel:[0,0,0] op_sel_hi:[1,0,1]
	v_pk_fma_f32 v[142:143], v[216:217], v[94:95], v[142:143] op_sel:[0,0,0] op_sel_hi:[1,0,1]
	v_pk_fma_f32 v[238:239], v[140:141], v[108:109], v[238:239] op_sel:[0,1,0] op_sel_hi:[1,1,1]
	v_pk_fma_f32 v[144:145], v[216:217], v[94:95], v[144:145] op_sel:[0,1,0] op_sel_hi:[1,1,1]
	v_pk_fma_f32 v[238:239], v[142:143], v[110:111], v[238:239] op_sel:[0,0,0] op_sel_hi:[1,0,1]
	ds_read_b128 v[88:91], v112 offset:25344
	v_pk_fma_f32 v[238:239], v[144:145], v[110:111], v[238:239] op_sel:[0,1,0] op_sel_hi:[1,1,1]
	ds_read_b128 v[92:95], v112 offset:25360
	ds_read_b128 v[96:99], v112 offset:8960
	v_add_f32_dpp v238, v238, v238 quad_perm:[1,0,3,2] row_mask:0xf bank_mask:0xf bound_ctrl:1
	v_add_f32_dpp v239, v239, v239 quad_perm:[1,0,3,2] row_mask:0xf bank_mask:0xf bound_ctrl:1
	ds_read_b128 v[100:103], v112 offset:8976
	v_add_f32_dpp v238, v238, v238 quad_perm:[2,3,0,1] row_mask:0xf bank_mask:0xf bound_ctrl:1
	v_add_f32_dpp v239, v239, v239 quad_perm:[2,3,0,1] row_mask:0xf bank_mask:0xf bound_ctrl:1
	ds_read_b128 v[104:107], v112 offset:33536
	v_add_f32_dpp v238, v238, v238 row_half_mirror row_mask:0xf bank_mask:0xf bound_ctrl:1
	v_add_f32_dpp v239, v239, v239 row_half_mirror row_mask:0xf bank_mask:0xf bound_ctrl:1
	ds_read_b128 v[108:111], v112 offset:33552
	ds_read_b64 v[148:149], v214 offset:41728
	s_and_saveexec_b64 s[36:37], s[8:9]
	ds_write_b64 v214, v[238:239] offset:49408
	s_or_b64 exec, exec, s[36:37]
	s_add_i32 s48, s48, 2
	v_add_u32_e32 v112, 0x200, v112
	v_add_u32_e32 v214, 0x200, v214
	s_cmp_lt_u32 s48, 32
	s_cbranch_scc1 .Lrwkv_step2
	ds_read_b128 v[8:11], v158 offset:7936
	ds_read_b128 v[12:15], v158 offset:7952
	s_waitcnt lgkmcnt(0)
	v_pk_mul_f32 v[130:131], v[130:131], v[8:9] op_sel:[0,0] op_sel_hi:[1,0]
	v_pk_mul_f32 v[132:133], v[132:133], v[8:9] op_sel:[0,1] op_sel_hi:[1,1]
	v_pk_mul_f32 v[134:135], v[134:135], v[10:11] op_sel:[0,0] op_sel_hi:[1,0]
	v_pk_mul_f32 v[136:137], v[136:137], v[10:11] op_sel:[0,1] op_sel_hi:[1,1]
	v_pk_mul_f32 v[138:139], v[138:139], v[12:13] op_sel:[0,0] op_sel_hi:[1,0]
	v_pk_mul_f32 v[140:141], v[140:141], v[12:13] op_sel:[0,1] op_sel_hi:[1,1]
	v_pk_mul_f32 v[142:143], v[142:143], v[14:15] op_sel:[0,0] op_sel_hi:[1,0]
	v_pk_mul_f32 v[144:145], v[144:145], v[14:15] op_sel:[0,1] op_sel_hi:[1,1]
	s_branch .LBB0_1599
